# P8 wide row pass software-pipelined (next row pair's loads issued before the current pair is computed)
# baseline (speedup 1.0000x reference)
; __device__ __forceinline__ float wave_sum(float v) { for (int o = 32; o >= 1; o >>= 1) v += __shfl_xor(v, o); return v; }
; __device__ __forceinline__ u32x2 pk4(f32x4 v) { u32x2 w; w.x = cvt_pk_bf16(v[0], v[1]); w.y = cvt_pk_bf16(v[2], v[3]); return w; }
; __device__ __forceinline__ f32x4 up4(u32x2 w) { return (f32x4){bf_lo(w.x), bf_hi(w.x), bf_lo(w.y), bf_hi(w.y)}; }
; __device__ __forceinline__ void row_pass1(const Args& a, int row_lo, int row_hi, int gw, int NGW, int lane) {
;     ...
;     for (int r0 = row_lo + 2 * gw; r0 < row_hi; r0 += 2 * NGW) {
;         f32x4 xv[2][4]; u32x2 yv[2][4]; float rs[2];
; #pragma unroll
;         for (int r = 0; r < 2; ++r) { const int row = (r0 + r < row_hi) ? r0 + r : r0; rs[r] = rss[row];
;             const f32x4* xr = (const f32x4*)xrow_ptr(a, row) + lane; const u32x2* yr = (const u32x2*)(Y + (size_t)row * DM) + lane;
; #pragma unroll
;             for (int j = 0; j < 4; ++j) { xv[r][j] = xr[64 * j]; yv[r][j] = yr[64 * j]; } }
; #pragma unroll
;         for (int r = 0; r < 2; ++r) { const int row = r0 + r; if (row >= row_hi) break;
;             const float rstd = rsqrtf(rs[r] * (1.f / DM) + EPS); f32x4 v[4]; float s = 0.f;
; #pragma unroll
;             for (int j = 0; j < 4; ++j) { v[j] = xv[r][j] + up4(yv[r][j]) * rstd * gp[j]; s += (v[j][0] * v[j][0] + v[j][1] * v[j][1]) + (v[j][2] * v[j][2] + v[j][3] * v[j][3]); }
;             const float rstd2 = rsqrtf(wave_sum(s) * (1.f / DM) + EPS);
;             f32x4* xo = (f32x4*)(XO + (size_t)row * DM) + lane; u32x2* ao = (u32x2*)(A2 + (size_t)row * DM) + lane;
; #pragma unroll
;             for (int j = 0; j < 4; ++j) { xo[64 * j] = v[j]; ao[64 * j] = pk4(v[j] * rstd2 * gq[j]); } }
.LBB0_1036:
	s_and_b64 vcc, exec, s[10:11]
	s_cbranch_vccz .LBB0_1042
	s_lshl_b32 s0, s81, 1
	s_add_i32 s8, s0, 0xffffff00
	s_cmpk_gt_i32 s8, 0x3fff
	s_cbranch_scc1 .LBB0_1042
	s_waitcnt vmcnt(0)
	v_readlane_b32 s20, v252, 1
	v_readlane_b32 s21, v252, 2
	v_readlane_b32 s14, v252, 13
	v_readlane_b32 s15, v252, 14
	v_readlane_b32 s18, v252, 15
	v_readlane_b32 s19, v252, 16
	v_lshlrev_b32_e32 v198, 4, v176
	v_lshlrev_b32_e32 v148, 5, v176
	v_add_u32_e32 v149, 0x1000, v148
	v_mov_b32_e32 v116, 0x358637bd
	v_mov_b32_e32 v197, 0
	s_lshl_b32 s1, s58, 4
	s_add_i32 s10, s1, 0xffffff00
	s_mov_b32 s0, s8
	s_ashr_i32 s1, s0, 31
	s_lshl_b64 s[22:23], s[0:1], 12
	global_load_dwordx4 v[84:87], v148, s[14:15]
	global_load_dwordx4 v[88:91], v148, s[14:15] offset:16
	global_load_dwordx4 v[92:95], v148, s[14:15] offset:2048
	global_load_dwordx4 v[96:99], v148, s[14:15] offset:2064
	global_load_dwordx4 v[180:183], v148, s[18:19]
	global_load_dwordx4 v[184:187], v148, s[18:19] offset:16
	global_load_dwordx4 v[188:191], v148, s[18:19] offset:2048
	global_load_dwordx4 v[192:195], v148, s[18:19] offset:2064
	s_add_u32 s20, s20, s22
	s_addc_u32 s21, s21, s23
	s_lshl_b64 s[22:23], s[0:1], 11
	s_add_u32 s24, s54, s22
	s_addc_u32 s25, s55, s23
	s_add_u32 s26, s24, 0x9a00000
	s_addc_u32 s27, s25, 0
	s_add_u32 s24, s24, 0xde00000
	s_addc_u32 s25, s25, 0
	s_lshl_b64 s[22:23], s[0:1], 2
	s_add_u32 s16, s54, s22
	s_addc_u32 s17, s55, s23
	s_add_u32 s16, s16, 0x2280000
	s_addc_u32 s17, s17, 0
	s_lshl_b32 s98, s10, 12
	s_lshl_b32 s99, s10, 11
	s_lshl_b32 s100, s10, 2
	s_mov_b32 s101, 0x800000
	global_load_dwordx2 v[80:81], v197, s[16:17]
	global_load_dwordx4 v[48:51], v198, s[24:25] nt
	global_load_dwordx4 v[52:55], v198, s[24:25] offset:1024 nt
	global_load_dwordx4 v[16:19], v148, s[20:21] nt
	global_load_dwordx4 v[20:23], v148, s[20:21] offset:16 nt
	global_load_dwordx4 v[24:27], v148, s[20:21] offset:2048 nt
	global_load_dwordx4 v[28:31], v148, s[20:21] offset:2064 nt
	global_load_dwordx4 v[56:59], v198, s[24:25] offset:2048 nt
	global_load_dwordx4 v[60:63], v198, s[24:25] offset:3072 nt
	global_load_dwordx4 v[32:35], v149, s[20:21] nt
	global_load_dwordx4 v[36:39], v149, s[20:21] offset:16 nt
	global_load_dwordx4 v[40:43], v149, s[20:21] offset:2048 nt
	global_load_dwordx4 v[44:47], v149, s[20:21] offset:2064 nt
	s_add_i32 s0, s0, s10
	s_add_u32 s20, s20, s98
	s_addc_u32 s21, s21, 0
	s_add_u32 s24, s24, s99
	s_addc_u32 s25, s25, 0
	s_add_u32 s16, s16, s100
	s_addc_u32 s17, s17, 0
.Lx8_half0:
	s_mov_b32 s11, 0
	s_cmpk_gt_i32 s0, 0x3fff
	s_cbranch_scc1 .Lx8_nonext0
	global_load_dwordx2 v[82:83], v197, s[16:17]
	global_load_dwordx4 v[228:231], v198, s[24:25] nt
	global_load_dwordx4 v[232:235], v198, s[24:25] offset:1024 nt
	global_load_dwordx4 v[0:3], v148, s[20:21] nt
	global_load_dwordx4 v[4:7], v148, s[20:21] offset:16 nt
	global_load_dwordx4 v[8:11], v148, s[20:21] offset:2048 nt
	global_load_dwordx4 v[12:15], v148, s[20:21] offset:2064 nt
	global_load_dwordx4 v[236:239], v198, s[24:25] offset:2048 nt
	global_load_dwordx4 v[240:243], v198, s[24:25] offset:3072 nt
	global_load_dwordx4 v[64:67], v149, s[20:21] nt
	global_load_dwordx4 v[68:71], v149, s[20:21] offset:16 nt
	global_load_dwordx4 v[72:75], v149, s[20:21] offset:2048 nt
	global_load_dwordx4 v[76:79], v149, s[20:21] offset:2064 nt
	s_add_i32 s0, s0, s10
	s_add_u32 s20, s20, s98
	s_addc_u32 s21, s21, 0
	s_add_u32 s24, s24, s99
	s_addc_u32 s25, s25, 0
	s_add_u32 s16, s16, s100
	s_addc_u32 s17, s17, 0
	s_mov_b32 s11, 1
	s_waitcnt vmcnt(19)
	s_branch .Lx8_rowA0
.Lx8_nonext0:
	s_waitcnt vmcnt(6)
.Lx8_rowA0:
	v_fmamk_f32 v104, v80, 0x3a800000, v116
	v_mul_f32_e32 v105, 0x4b800000, v104
	v_cmp_gt_f32_e32 vcc, s101, v104
	s_nop 1
	v_cndmask_b32_e32 v104, v104, v105, vcc
	v_rsq_f32_e32 v104, v104
	s_nop 0
	v_mul_f32_e32 v105, 0x45800000, v104
	v_cndmask_b32_e32 v104, v104, v105, vcc
	v_lshlrev_b32_e32 v120, 16, v48
	v_and_b32_e32 v121, 0xffff0000, v48
	v_lshlrev_b32_e32 v122, 16, v49
	v_and_b32_e32 v123, 0xffff0000, v49
	v_pk_mul_f32 v[120:121], v[104:105], v[120:121] op_sel_hi:[0,1]
	v_pk_mul_f32 v[122:123], v[104:105], v[122:123] op_sel_hi:[0,1]
	v_pk_fma_f32 v[16:17], v[84:85], v[120:121], v[16:17]
	v_pk_fma_f32 v[18:19], v[86:87], v[122:123], v[18:19]
	v_lshlrev_b32_e32 v124, 16, v50
	v_and_b32_e32 v125, 0xffff0000, v50
	v_lshlrev_b32_e32 v126, 16, v51
	v_and_b32_e32 v127, 0xffff0000, v51
	v_pk_mul_f32 v[124:125], v[104:105], v[124:125] op_sel_hi:[0,1]
	v_pk_mul_f32 v[126:127], v[104:105], v[126:127] op_sel_hi:[0,1]
	v_pk_fma_f32 v[20:21], v[88:89], v[124:125], v[20:21]
	v_pk_fma_f32 v[22:23], v[90:91], v[126:127], v[22:23]
	v_lshlrev_b32_e32 v128, 16, v52
	v_and_b32_e32 v129, 0xffff0000, v52
	v_lshlrev_b32_e32 v130, 16, v53
	v_and_b32_e32 v131, 0xffff0000, v53
	v_pk_mul_f32 v[128:129], v[104:105], v[128:129] op_sel_hi:[0,1]
	v_pk_mul_f32 v[130:131], v[104:105], v[130:131] op_sel_hi:[0,1]
	v_pk_fma_f32 v[24:25], v[92:93], v[128:129], v[24:25]
	v_pk_fma_f32 v[26:27], v[94:95], v[130:131], v[26:27]
	v_lshlrev_b32_e32 v132, 16, v54
	v_and_b32_e32 v133, 0xffff0000, v54
	v_lshlrev_b32_e32 v134, 16, v55
	v_and_b32_e32 v135, 0xffff0000, v55
	v_pk_mul_f32 v[132:133], v[104:105], v[132:133] op_sel_hi:[0,1]
	v_pk_mul_f32 v[134:135], v[104:105], v[134:135] op_sel_hi:[0,1]
	v_pk_fma_f32 v[28:29], v[96:97], v[132:133], v[28:29]
	v_pk_fma_f32 v[30:31], v[98:99], v[134:135], v[30:31]
	v_pk_mul_f32 v[200:201], v[16:17], v[16:17]
	v_pk_fma_f32 v[200:201], v[18:19], v[18:19], v[200:201]
	v_pk_mul_f32 v[202:203], v[20:21], v[20:21]
	v_pk_fma_f32 v[202:203], v[22:23], v[22:23], v[202:203]
	v_pk_add_f32 v[200:201], v[200:201], v[202:203]
; __device__ __forceinline__ float wave_sum(float v) { for (int o = 32; o >= 1; o >>= 1) v += __shfl_xor(v, o); return v; }
; __device__ __forceinline__ u32x2 pk4(f32x4 v) { u32x2 w; w.x = cvt_pk_bf16(v[0], v[1]); w.y = cvt_pk_bf16(v[2], v[3]); return w; }
; __device__ __forceinline__ f32x4 up4(u32x2 w) { return (f32x4){bf_lo(w.x), bf_hi(w.x), bf_lo(w.y), bf_hi(w.y)}; }
; __device__ __forceinline__ void row_pass1(const Args& a, int row_lo, int row_hi, int gw, int NGW, int lane) {
;     ...
;         for (int r = 0; r < 2; ++r) { const int row = r0 + r; if (row >= row_hi) break;
;             const float rstd = rsqrtf(rs[r] * (1.f / DM) + EPS); f32x4 v[4]; float s = 0.f;
; #pragma unroll
;             for (int j = 0; j < 4; ++j) { v[j] = xv[r][j] + up4(yv[r][j]) * rstd * gp[j]; s += (v[j][0] * v[j][0] + v[j][1] * v[j][1]) + (v[j][2] * v[j][2] + v[j][3] * v[j][3]); }
;             const float rstd2 = rsqrtf(wave_sum(s) * (1.f / DM) + EPS);
;             f32x4* xo = (f32x4*)(XO + (size_t)row * DM) + lane; u32x2* ao = (u32x2*)(A2 + (size_t)row * DM) + lane;
; #pragma unroll
;             for (int j = 0; j < 4; ++j) { xo[64 * j] = v[j]; ao[64 * j] = pk4(v[j] * rstd2 * gq[j]); } }
	v_pk_mul_f32 v[202:203], v[24:25], v[24:25]
	v_pk_fma_f32 v[202:203], v[26:27], v[26:27], v[202:203]
	v_pk_add_f32 v[200:201], v[200:201], v[202:203]
	v_pk_mul_f32 v[202:203], v[28:29], v[28:29]
	v_pk_fma_f32 v[202:203], v[30:31], v[30:31], v[202:203]
	v_pk_add_f32 v[200:201], v[200:201], v[202:203]
	v_add_f32_e32 v200, v200, v201
	s_nop 1
	v_add_f32_dpp v200, v200, v200 quad_perm:[1,0,3,2] row_mask:0xf bank_mask:0xf
	s_nop 1
	v_add_f32_dpp v200, v200, v200 quad_perm:[2,3,0,1] row_mask:0xf bank_mask:0xf
	s_nop 1
	v_add_f32_dpp v200, v200, v200 row_half_mirror row_mask:0xf bank_mask:0xf
	s_nop 1
	v_add_f32_dpp v200, v200, v200 row_mirror row_mask:0xf bank_mask:0xf
	v_mov_b32_e32 v201, v200
	s_nop 1
	v_permlane16_swap_b32_e32 v200, v201
	v_add_f32_e32 v200, v200, v201
	v_mov_b32_e32 v201, v200
	s_nop 1
	v_permlane32_swap_b32_e32 v200, v201
	v_add_f32_e32 v200, v200, v201
	v_fmamk_f32 v106, v200, 0x3a800000, v116
	v_mul_f32_e32 v107, 0x4b800000, v106
	v_cmp_gt_f32_e32 vcc, s101, v106
	s_nop 1
	v_cndmask_b32_e32 v106, v106, v107, vcc
	v_rsq_f32_e32 v106, v106
	s_nop 0
	v_mul_f32_e32 v107, 0x45800000, v106
	v_cndmask_b32_e32 v106, v106, v107, vcc
	v_pk_mul_f32 v[204:205], v[16:17], v[106:107] op_sel_hi:[1,0]
	v_pk_mul_f32 v[206:207], v[18:19], v[106:107] op_sel_hi:[1,0]
	v_pk_mul_f32 v[204:205], v[180:181], v[204:205]
	v_pk_mul_f32 v[206:207], v[182:183], v[206:207]
	v_pk_mul_f32 v[208:209], v[20:21], v[106:107] op_sel_hi:[1,0]
	v_pk_mul_f32 v[210:211], v[22:23], v[106:107] op_sel_hi:[1,0]
	v_pk_mul_f32 v[208:209], v[184:185], v[208:209]
	v_pk_mul_f32 v[210:211], v[186:187], v[210:211]
	v_pk_mul_f32 v[212:213], v[24:25], v[106:107] op_sel_hi:[1,0]
	v_pk_mul_f32 v[214:215], v[26:27], v[106:107] op_sel_hi:[1,0]
	v_pk_mul_f32 v[212:213], v[188:189], v[212:213]
	v_pk_mul_f32 v[214:215], v[190:191], v[214:215]
	v_pk_mul_f32 v[216:217], v[28:29], v[106:107] op_sel_hi:[1,0]
	v_pk_mul_f32 v[218:219], v[30:31], v[106:107] op_sel_hi:[1,0]
	v_pk_mul_f32 v[216:217], v[192:193], v[216:217]
	v_pk_mul_f32 v[218:219], v[194:195], v[218:219]
	v_cvt_pk_bf16_f32 v220, v204, v205
	v_cvt_pk_bf16_f32 v221, v206, v207
	v_cvt_pk_bf16_f32 v222, v208, v209
	v_cvt_pk_bf16_f32 v223, v210, v211
	v_cvt_pk_bf16_f32 v224, v212, v213
	v_cvt_pk_bf16_f32 v225, v214, v215
	v_cvt_pk_bf16_f32 v226, v216, v217
	v_cvt_pk_bf16_f32 v227, v218, v219
	global_store_dwordx4 v198, v[220:223], s[26:27]
	global_store_dwordx4 v198, v[224:227], s[26:27] offset:1024
	s_cmp_lg_u32 s11, 0
	s_cbranch_scc1 .Lx8_wB0
	s_waitcnt vmcnt(2)
	s_branch .Lx8_rowB0
.Lx8_wB0:
	s_waitcnt vmcnt(15)
; __device__ __forceinline__ float wave_sum(float v) { for (int o = 32; o >= 1; o >>= 1) v += __shfl_xor(v, o); return v; }
; __device__ __forceinline__ u32x2 pk4(f32x4 v) { u32x2 w; w.x = cvt_pk_bf16(v[0], v[1]); w.y = cvt_pk_bf16(v[2], v[3]); return w; }
; __device__ __forceinline__ f32x4 up4(u32x2 w) { return (f32x4){bf_lo(w.x), bf_hi(w.x), bf_lo(w.y), bf_hi(w.y)}; }
; __device__ __forceinline__ void row_pass1(const Args& a, int row_lo, int row_hi, int gw, int NGW, int lane) {
;     ...
;         for (int r = 0; r < 2; ++r) { const int row = r0 + r; if (row >= row_hi) break;
;             const float rstd = rsqrtf(rs[r] * (1.f / DM) + EPS); f32x4 v[4]; float s = 0.f;
; #pragma unroll
;             for (int j = 0; j < 4; ++j) { v[j] = xv[r][j] + up4(yv[r][j]) * rstd * gp[j]; s += (v[j][0] * v[j][0] + v[j][1] * v[j][1]) + (v[j][2] * v[j][2] + v[j][3] * v[j][3]); }
;             const float rstd2 = rsqrtf(wave_sum(s) * (1.f / DM) + EPS);
;             f32x4* xo = (f32x4*)(XO + (size_t)row * DM) + lane; u32x2* ao = (u32x2*)(A2 + (size_t)row * DM) + lane;
; #pragma unroll
;             for (int j = 0; j < 4; ++j) { xo[64 * j] = v[j]; ao[64 * j] = pk4(v[j] * rstd2 * gq[j]); } }
.Lx8_rowB0:
	v_fmamk_f32 v104, v81, 0x3a800000, v116
	v_mul_f32_e32 v105, 0x4b800000, v104
	v_cmp_gt_f32_e32 vcc, s101, v104
	s_nop 1
	v_cndmask_b32_e32 v104, v104, v105, vcc
	v_rsq_f32_e32 v104, v104
	s_nop 0
	v_mul_f32_e32 v105, 0x45800000, v104
	v_cndmask_b32_e32 v104, v104, v105, vcc
	v_lshlrev_b32_e32 v120, 16, v56
	v_and_b32_e32 v121, 0xffff0000, v56
	v_lshlrev_b32_e32 v122, 16, v57
	v_and_b32_e32 v123, 0xffff0000, v57
	v_pk_mul_f32 v[120:121], v[104:105], v[120:121] op_sel_hi:[0,1]
	v_pk_mul_f32 v[122:123], v[104:105], v[122:123] op_sel_hi:[0,1]
	v_pk_fma_f32 v[32:33], v[84:85], v[120:121], v[32:33]
	v_pk_fma_f32 v[34:35], v[86:87], v[122:123], v[34:35]
	v_lshlrev_b32_e32 v124, 16, v58
	v_and_b32_e32 v125, 0xffff0000, v58
	v_lshlrev_b32_e32 v126, 16, v59
	v_and_b32_e32 v127, 0xffff0000, v59
	v_pk_mul_f32 v[124:125], v[104:105], v[124:125] op_sel_hi:[0,1]
	v_pk_mul_f32 v[126:127], v[104:105], v[126:127] op_sel_hi:[0,1]
	v_pk_fma_f32 v[36:37], v[88:89], v[124:125], v[36:37]
	v_pk_fma_f32 v[38:39], v[90:91], v[126:127], v[38:39]
	v_lshlrev_b32_e32 v128, 16, v60
	v_and_b32_e32 v129, 0xffff0000, v60
	v_lshlrev_b32_e32 v130, 16, v61
	v_and_b32_e32 v131, 0xffff0000, v61
	v_pk_mul_f32 v[128:129], v[104:105], v[128:129] op_sel_hi:[0,1]
	v_pk_mul_f32 v[130:131], v[104:105], v[130:131] op_sel_hi:[0,1]
	v_pk_fma_f32 v[40:41], v[92:93], v[128:129], v[40:41]
	v_pk_fma_f32 v[42:43], v[94:95], v[130:131], v[42:43]
	v_lshlrev_b32_e32 v132, 16, v62
	v_and_b32_e32 v133, 0xffff0000, v62
	v_lshlrev_b32_e32 v134, 16, v63
	v_and_b32_e32 v135, 0xffff0000, v63
	v_pk_mul_f32 v[132:133], v[104:105], v[132:133] op_sel_hi:[0,1]
	v_pk_mul_f32 v[134:135], v[104:105], v[134:135] op_sel_hi:[0,1]
	v_pk_fma_f32 v[44:45], v[96:97], v[132:133], v[44:45]
	v_pk_fma_f32 v[46:47], v[98:99], v[134:135], v[46:47]
	v_pk_mul_f32 v[200:201], v[32:33], v[32:33]
	v_pk_fma_f32 v[200:201], v[34:35], v[34:35], v[200:201]
	v_pk_mul_f32 v[202:203], v[36:37], v[36:37]
	v_pk_fma_f32 v[202:203], v[38:39], v[38:39], v[202:203]
	v_pk_add_f32 v[200:201], v[200:201], v[202:203]
	v_pk_mul_f32 v[202:203], v[40:41], v[40:41]
	v_pk_fma_f32 v[202:203], v[42:43], v[42:43], v[202:203]
	v_pk_add_f32 v[200:201], v[200:201], v[202:203]
	v_pk_mul_f32 v[202:203], v[44:45], v[44:45]
	v_pk_fma_f32 v[202:203], v[46:47], v[46:47], v[202:203]
	v_pk_add_f32 v[200:201], v[200:201], v[202:203]
	v_add_f32_e32 v200, v200, v201
	s_nop 1
	v_add_f32_dpp v200, v200, v200 quad_perm:[1,0,3,2] row_mask:0xf bank_mask:0xf
	s_nop 1
	v_add_f32_dpp v200, v200, v200 quad_perm:[2,3,0,1] row_mask:0xf bank_mask:0xf
	s_nop 1
	v_add_f32_dpp v200, v200, v200 row_half_mirror row_mask:0xf bank_mask:0xf
	s_nop 1
	v_add_f32_dpp v200, v200, v200 row_mirror row_mask:0xf bank_mask:0xf
	v_mov_b32_e32 v201, v200
	s_nop 1
	v_permlane16_swap_b32_e32 v200, v201
	v_add_f32_e32 v200, v200, v201
	v_mov_b32_e32 v201, v200
	s_nop 1
	v_permlane32_swap_b32_e32 v200, v201
	v_add_f32_e32 v200, v200, v201
	v_fmamk_f32 v106, v200, 0x3a800000, v116
	v_mul_f32_e32 v107, 0x4b800000, v106
	v_cmp_gt_f32_e32 vcc, s101, v106
	s_nop 1
	v_cndmask_b32_e32 v106, v106, v107, vcc
	v_rsq_f32_e32 v106, v106
	s_nop 0
	v_mul_f32_e32 v107, 0x45800000, v106
	v_cndmask_b32_e32 v106, v106, v107, vcc
	v_pk_mul_f32 v[204:205], v[32:33], v[106:107] op_sel_hi:[1,0]
	v_pk_mul_f32 v[206:207], v[34:35], v[106:107] op_sel_hi:[1,0]
	v_pk_mul_f32 v[204:205], v[180:181], v[204:205]
	v_pk_mul_f32 v[206:207], v[182:183], v[206:207]
	v_pk_mul_f32 v[208:209], v[36:37], v[106:107] op_sel_hi:[1,0]
	v_pk_mul_f32 v[210:211], v[38:39], v[106:107] op_sel_hi:[1,0]
	v_pk_mul_f32 v[208:209], v[184:185], v[208:209]
	v_pk_mul_f32 v[210:211], v[186:187], v[210:211]
	v_pk_mul_f32 v[212:213], v[40:41], v[106:107] op_sel_hi:[1,0]
	v_pk_mul_f32 v[214:215], v[42:43], v[106:107] op_sel_hi:[1,0]
	v_pk_mul_f32 v[212:213], v[188:189], v[212:213]
	v_pk_mul_f32 v[214:215], v[190:191], v[214:215]
	v_pk_mul_f32 v[216:217], v[44:45], v[106:107] op_sel_hi:[1,0]
	v_pk_mul_f32 v[218:219], v[46:47], v[106:107] op_sel_hi:[1,0]
	v_pk_mul_f32 v[216:217], v[192:193], v[216:217]
	v_pk_mul_f32 v[218:219], v[194:195], v[218:219]
	v_cvt_pk_bf16_f32 v220, v204, v205
	v_cvt_pk_bf16_f32 v221, v206, v207
	v_cvt_pk_bf16_f32 v222, v208, v209
	v_cvt_pk_bf16_f32 v223, v210, v211
	v_cvt_pk_bf16_f32 v224, v212, v213
	v_cvt_pk_bf16_f32 v225, v214, v215
	v_cvt_pk_bf16_f32 v226, v216, v217
	v_cvt_pk_bf16_f32 v227, v218, v219
	global_store_dwordx4 v198, v[220:223], s[26:27] offset:2048
	global_store_dwordx4 v198, v[224:227], s[26:27] offset:3072
	s_add_u32 s26, s26, s99
	s_addc_u32 s27, s27, 0
	s_cmp_lg_u32 s11, 0
	s_cbranch_scc0 .Lx8_done
.Lx8_half1:
	s_mov_b32 s11, 0
	s_cmpk_gt_i32 s0, 0x3fff
	s_cbranch_scc1 .Lx8_nonext1
	global_load_dwordx2 v[80:81], v197, s[16:17]
	global_load_dwordx4 v[48:51], v198, s[24:25] nt
	global_load_dwordx4 v[52:55], v198, s[24:25] offset:1024 nt
	global_load_dwordx4 v[16:19], v148, s[20:21] nt
	global_load_dwordx4 v[20:23], v148, s[20:21] offset:16 nt
	global_load_dwordx4 v[24:27], v148, s[20:21] offset:2048 nt
	global_load_dwordx4 v[28:31], v148, s[20:21] offset:2064 nt
	global_load_dwordx4 v[56:59], v198, s[24:25] offset:2048 nt
	global_load_dwordx4 v[60:63], v198, s[24:25] offset:3072 nt
	global_load_dwordx4 v[32:35], v149, s[20:21] nt
	global_load_dwordx4 v[36:39], v149, s[20:21] offset:16 nt
	global_load_dwordx4 v[40:43], v149, s[20:21] offset:2048 nt
	global_load_dwordx4 v[44:47], v149, s[20:21] offset:2064 nt
	s_add_i32 s0, s0, s10
	s_add_u32 s20, s20, s98
	s_addc_u32 s21, s21, 0
	s_add_u32 s24, s24, s99
	s_addc_u32 s25, s25, 0
	s_add_u32 s16, s16, s100
	s_addc_u32 s17, s17, 0
	s_mov_b32 s11, 1
	s_waitcnt vmcnt(19)
	s_branch .Lx8_rowA1

; __device__ __forceinline__ float wave_sum(float v) { for (int o = 32; o >= 1; o >>= 1) v += __shfl_xor(v, o); return v; }
; __device__ __forceinline__ u32x2 pk4(f32x4 v) { u32x2 w; w.x = cvt_pk_bf16(v[0], v[1]); w.y = cvt_pk_bf16(v[2], v[3]); return w; }
; __device__ __forceinline__ f32x4 up4(u32x2 w) { return (f32x4){bf_lo(w.x), bf_hi(w.x), bf_lo(w.y), bf_hi(w.y)}; }
; __device__ __forceinline__ void row_pass1(const Args& a, int row_lo, int row_hi, int gw, int NGW, int lane) {
;     ...
;         for (int r = 0; r < 2; ++r) { const int row = r0 + r; if (row >= row_hi) break;
;             const float rstd = rsqrtf(rs[r] * (1.f / DM) + EPS); f32x4 v[4]; float s = 0.f;
; #pragma unroll
;             for (int j = 0; j < 4; ++j) { v[j] = xv[r][j] + up4(yv[r][j]) * rstd * gp[j]; s += (v[j][0] * v[j][0] + v[j][1] * v[j][1]) + (v[j][2] * v[j][2] + v[j][3] * v[j][3]); }
;             const float rstd2 = rsqrtf(wave_sum(s) * (1.f / DM) + EPS);
;             f32x4* xo = (f32x4*)(XO + (size_t)row * DM) + lane; u32x2* ao = (u32x2*)(A2 + (size_t)row * DM) + lane;
; #pragma unroll
;             for (int j = 0; j < 4; ++j) { xo[64 * j] = v[j]; ao[64 * j] = pk4(v[j] * rstd2 * gq[j]); } }
.Lx8_rowA1:
	v_fmamk_f32 v104, v82, 0x3a800000, v116
	v_mul_f32_e32 v105, 0x4b800000, v104
	v_cmp_gt_f32_e32 vcc, s101, v104
	s_nop 1
	v_cndmask_b32_e32 v104, v104, v105, vcc
	v_rsq_f32_e32 v104, v104
	s_nop 0
	v_mul_f32_e32 v105, 0x45800000, v104
	v_cndmask_b32_e32 v104, v104, v105, vcc
	v_lshlrev_b32_e32 v120, 16, v228
	v_and_b32_e32 v121, 0xffff0000, v228
	v_lshlrev_b32_e32 v122, 16, v229
	v_and_b32_e32 v123, 0xffff0000, v229
	v_pk_mul_f32 v[120:121], v[104:105], v[120:121] op_sel_hi:[0,1]
	v_pk_mul_f32 v[122:123], v[104:105], v[122:123] op_sel_hi:[0,1]
	v_pk_fma_f32 v[0:1], v[84:85], v[120:121], v[0:1]
	v_pk_fma_f32 v[2:3], v[86:87], v[122:123], v[2:3]
	v_lshlrev_b32_e32 v124, 16, v230
	v_and_b32_e32 v125, 0xffff0000, v230
	v_lshlrev_b32_e32 v126, 16, v231
	v_and_b32_e32 v127, 0xffff0000, v231
	v_pk_mul_f32 v[124:125], v[104:105], v[124:125] op_sel_hi:[0,1]
	v_pk_mul_f32 v[126:127], v[104:105], v[126:127] op_sel_hi:[0,1]
	v_pk_fma_f32 v[4:5], v[88:89], v[124:125], v[4:5]
	v_pk_fma_f32 v[6:7], v[90:91], v[126:127], v[6:7]
	v_lshlrev_b32_e32 v128, 16, v232
	v_and_b32_e32 v129, 0xffff0000, v232
	v_lshlrev_b32_e32 v130, 16, v233
	v_and_b32_e32 v131, 0xffff0000, v233
	v_pk_mul_f32 v[128:129], v[104:105], v[128:129] op_sel_hi:[0,1]
	v_pk_mul_f32 v[130:131], v[104:105], v[130:131] op_sel_hi:[0,1]
	v_pk_fma_f32 v[8:9], v[92:93], v[128:129], v[8:9]
	v_pk_fma_f32 v[10:11], v[94:95], v[130:131], v[10:11]
	v_lshlrev_b32_e32 v132, 16, v234
	v_and_b32_e32 v133, 0xffff0000, v234
	v_lshlrev_b32_e32 v134, 16, v235
	v_and_b32_e32 v135, 0xffff0000, v235
	v_pk_mul_f32 v[132:133], v[104:105], v[132:133] op_sel_hi:[0,1]
	v_pk_mul_f32 v[134:135], v[104:105], v[134:135] op_sel_hi:[0,1]
	v_pk_fma_f32 v[12:13], v[96:97], v[132:133], v[12:13]
	v_pk_fma_f32 v[14:15], v[98:99], v[134:135], v[14:15]
	v_pk_mul_f32 v[200:201], v[0:1], v[0:1]
	v_pk_fma_f32 v[200:201], v[2:3], v[2:3], v[200:201]
	v_pk_mul_f32 v[202:203], v[4:5], v[4:5]
	v_pk_fma_f32 v[202:203], v[6:7], v[6:7], v[202:203]
	v_pk_add_f32 v[200:201], v[200:201], v[202:203]
	v_pk_mul_f32 v[202:203], v[8:9], v[8:9]
	v_pk_fma_f32 v[202:203], v[10:11], v[10:11], v[202:203]
	v_pk_add_f32 v[200:201], v[200:201], v[202:203]
	v_pk_mul_f32 v[202:203], v[12:13], v[12:13]
	v_pk_fma_f32 v[202:203], v[14:15], v[14:15], v[202:203]
	v_pk_add_f32 v[200:201], v[200:201], v[202:203]
	v_add_f32_e32 v200, v200, v201
	s_nop 1
	v_add_f32_dpp v200, v200, v200 quad_perm:[1,0,3,2] row_mask:0xf bank_mask:0xf
	s_nop 1
	v_add_f32_dpp v200, v200, v200 quad_perm:[2,3,0,1] row_mask:0xf bank_mask:0xf
	s_nop 1
	v_add_f32_dpp v200, v200, v200 row_half_mirror row_mask:0xf bank_mask:0xf
	s_nop 1
	v_add_f32_dpp v200, v200, v200 row_mirror row_mask:0xf bank_mask:0xf
	v_mov_b32_e32 v201, v200
	s_nop 1
	v_permlane16_swap_b32_e32 v200, v201
	v_add_f32_e32 v200, v200, v201
	v_mov_b32_e32 v201, v200
	s_nop 1
	v_permlane32_swap_b32_e32 v200, v201
	v_add_f32_e32 v200, v200, v201
	v_fmamk_f32 v106, v200, 0x3a800000, v116
	v_mul_f32_e32 v107, 0x4b800000, v106
	v_cmp_gt_f32_e32 vcc, s101, v106
	s_nop 1
	v_cndmask_b32_e32 v106, v106, v107, vcc
	v_rsq_f32_e32 v106, v106
	s_nop 0
	v_mul_f32_e32 v107, 0x45800000, v106
	v_cndmask_b32_e32 v106, v106, v107, vcc
	v_pk_mul_f32 v[204:205], v[0:1], v[106:107] op_sel_hi:[1,0]
	v_pk_mul_f32 v[206:207], v[2:3], v[106:107] op_sel_hi:[1,0]
	v_pk_mul_f32 v[204:205], v[180:181], v[204:205]
	v_pk_mul_f32 v[206:207], v[182:183], v[206:207]
	v_pk_mul_f32 v[208:209], v[4:5], v[106:107] op_sel_hi:[1,0]
	v_pk_mul_f32 v[210:211], v[6:7], v[106:107] op_sel_hi:[1,0]
	v_pk_mul_f32 v[208:209], v[184:185], v[208:209]
	v_pk_mul_f32 v[210:211], v[186:187], v[210:211]
	v_pk_mul_f32 v[212:213], v[8:9], v[106:107] op_sel_hi:[1,0]
	v_pk_mul_f32 v[214:215], v[10:11], v[106:107] op_sel_hi:[1,0]
	v_pk_mul_f32 v[212:213], v[188:189], v[212:213]
	v_pk_mul_f32 v[214:215], v[190:191], v[214:215]
	v_pk_mul_f32 v[216:217], v[12:13], v[106:107] op_sel_hi:[1,0]
	v_pk_mul_f32 v[218:219], v[14:15], v[106:107] op_sel_hi:[1,0]
	v_pk_mul_f32 v[216:217], v[192:193], v[216:217]
	v_pk_mul_f32 v[218:219], v[194:195], v[218:219]
	v_cvt_pk_bf16_f32 v220, v204, v205
	v_cvt_pk_bf16_f32 v221, v206, v207
	v_cvt_pk_bf16_f32 v222, v208, v209
	v_cvt_pk_bf16_f32 v223, v210, v211
	v_cvt_pk_bf16_f32 v224, v212, v213
	v_cvt_pk_bf16_f32 v225, v214, v215
	v_cvt_pk_bf16_f32 v226, v216, v217
	v_cvt_pk_bf16_f32 v227, v218, v219
	global_store_dwordx4 v198, v[220:223], s[26:27]
	global_store_dwordx4 v198, v[224:227], s[26:27] offset:1024
	s_cmp_lg_u32 s11, 0
	s_cbranch_scc1 .Lx8_wB1
	s_waitcnt vmcnt(2)
	s_branch .Lx8_rowB1

; __device__ __forceinline__ float wave_sum(float v) { for (int o = 32; o >= 1; o >>= 1) v += __shfl_xor(v, o); return v; }
; __device__ __forceinline__ u32x2 pk4(f32x4 v) { u32x2 w; w.x = cvt_pk_bf16(v[0], v[1]); w.y = cvt_pk_bf16(v[2], v[3]); return w; }
; __device__ __forceinline__ f32x4 up4(u32x2 w) { return (f32x4){bf_lo(w.x), bf_hi(w.x), bf_lo(w.y), bf_hi(w.y)}; }
; __device__ __forceinline__ void row_pass1(const Args& a, int row_lo, int row_hi, int gw, int NGW, int lane) {
;     ...
;         for (int r = 0; r < 2; ++r) { const int row = r0 + r; if (row >= row_hi) break;
;             const float rstd = rsqrtf(rs[r] * (1.f / DM) + EPS); f32x4 v[4]; float s = 0.f;
; #pragma unroll
;             for (int j = 0; j < 4; ++j) { v[j] = xv[r][j] + up4(yv[r][j]) * rstd * gp[j]; s += (v[j][0] * v[j][0] + v[j][1] * v[j][1]) + (v[j][2] * v[j][2] + v[j][3] * v[j][3]); }
;             const float rstd2 = rsqrtf(wave_sum(s) * (1.f / DM) + EPS);
;             f32x4* xo = (f32x4*)(XO + (size_t)row * DM) + lane; u32x2* ao = (u32x2*)(A2 + (size_t)row * DM) + lane;
; #pragma unroll
;             for (int j = 0; j < 4; ++j) { xo[64 * j] = v[j]; ao[64 * j] = pk4(v[j] * rstd2 * gq[j]); } }
.Lx8_rowB1:
	v_fmamk_f32 v104, v83, 0x3a800000, v116
	v_mul_f32_e32 v105, 0x4b800000, v104
	v_cmp_gt_f32_e32 vcc, s101, v104
	s_nop 1
	v_cndmask_b32_e32 v104, v104, v105, vcc
	v_rsq_f32_e32 v104, v104
	s_nop 0
	v_mul_f32_e32 v105, 0x45800000, v104
	v_cndmask_b32_e32 v104, v104, v105, vcc
	v_lshlrev_b32_e32 v120, 16, v236
	v_and_b32_e32 v121, 0xffff0000, v236
	v_lshlrev_b32_e32 v122, 16, v237
	v_and_b32_e32 v123, 0xffff0000, v237
	v_pk_mul_f32 v[120:121], v[104:105], v[120:121] op_sel_hi:[0,1]
	v_pk_mul_f32 v[122:123], v[104:105], v[122:123] op_sel_hi:[0,1]
	v_pk_fma_f32 v[64:65], v[84:85], v[120:121], v[64:65]
	v_pk_fma_f32 v[66:67], v[86:87], v[122:123], v[66:67]
	v_lshlrev_b32_e32 v124, 16, v238
	v_and_b32_e32 v125, 0xffff0000, v238
	v_lshlrev_b32_e32 v126, 16, v239
	v_and_b32_e32 v127, 0xffff0000, v239
	v_pk_mul_f32 v[124:125], v[104:105], v[124:125] op_sel_hi:[0,1]
	v_pk_mul_f32 v[126:127], v[104:105], v[126:127] op_sel_hi:[0,1]
	v_pk_fma_f32 v[68:69], v[88:89], v[124:125], v[68:69]
	v_pk_fma_f32 v[70:71], v[90:91], v[126:127], v[70:71]
	v_lshlrev_b32_e32 v128, 16, v240
	v_and_b32_e32 v129, 0xffff0000, v240
	v_lshlrev_b32_e32 v130, 16, v241
	v_and_b32_e32 v131, 0xffff0000, v241
	v_pk_mul_f32 v[128:129], v[104:105], v[128:129] op_sel_hi:[0,1]
	v_pk_mul_f32 v[130:131], v[104:105], v[130:131] op_sel_hi:[0,1]
	v_pk_fma_f32 v[72:73], v[92:93], v[128:129], v[72:73]
	v_pk_fma_f32 v[74:75], v[94:95], v[130:131], v[74:75]
	v_lshlrev_b32_e32 v132, 16, v242
	v_and_b32_e32 v133, 0xffff0000, v242
	v_lshlrev_b32_e32 v134, 16, v243
	v_and_b32_e32 v135, 0xffff0000, v243
	v_pk_mul_f32 v[132:133], v[104:105], v[132:133] op_sel_hi:[0,1]
	v_pk_mul_f32 v[134:135], v[104:105], v[134:135] op_sel_hi:[0,1]
	v_pk_fma_f32 v[76:77], v[96:97], v[132:133], v[76:77]
	v_pk_fma_f32 v[78:79], v[98:99], v[134:135], v[78:79]
	v_pk_mul_f32 v[200:201], v[64:65], v[64:65]
	v_pk_fma_f32 v[200:201], v[66:67], v[66:67], v[200:201]
	v_pk_mul_f32 v[202:203], v[68:69], v[68:69]
	v_pk_fma_f32 v[202:203], v[70:71], v[70:71], v[202:203]
	v_pk_add_f32 v[200:201], v[200:201], v[202:203]
	v_pk_mul_f32 v[202:203], v[72:73], v[72:73]
	v_pk_fma_f32 v[202:203], v[74:75], v[74:75], v[202:203]
	v_pk_add_f32 v[200:201], v[200:201], v[202:203]
	v_pk_mul_f32 v[202:203], v[76:77], v[76:77]
	v_pk_fma_f32 v[202:203], v[78:79], v[78:79], v[202:203]
	v_pk_add_f32 v[200:201], v[200:201], v[202:203]
	v_add_f32_e32 v200, v200, v201
	s_nop 1
	v_add_f32_dpp v200, v200, v200 quad_perm:[1,0,3,2] row_mask:0xf bank_mask:0xf
	s_nop 1
	v_add_f32_dpp v200, v200, v200 quad_perm:[2,3,0,1] row_mask:0xf bank_mask:0xf
	s_nop 1
	v_add_f32_dpp v200, v200, v200 row_half_mirror row_mask:0xf bank_mask:0xf
	s_nop 1
	v_add_f32_dpp v200, v200, v200 row_mirror row_mask:0xf bank_mask:0xf
	v_mov_b32_e32 v201, v200
	s_nop 1
	v_permlane16_swap_b32_e32 v200, v201
	v_add_f32_e32 v200, v200, v201
	v_mov_b32_e32 v201, v200
	s_nop 1
	v_permlane32_swap_b32_e32 v200, v201
	v_add_f32_e32 v200, v200, v201
	v_fmamk_f32 v106, v200, 0x3a800000, v116
	v_mul_f32_e32 v107, 0x4b800000, v106
	v_cmp_gt_f32_e32 vcc, s101, v106
	s_nop 1
	v_cndmask_b32_e32 v106, v106, v107, vcc
	v_rsq_f32_e32 v106, v106
	s_nop 0
	v_mul_f32_e32 v107, 0x45800000, v106
	v_cndmask_b32_e32 v106, v106, v107, vcc
	v_pk_mul_f32 v[204:205], v[64:65], v[106:107] op_sel_hi:[1,0]
	v_pk_mul_f32 v[206:207], v[66:67], v[106:107] op_sel_hi:[1,0]
	v_pk_mul_f32 v[204:205], v[180:181], v[204:205]
	v_pk_mul_f32 v[206:207], v[182:183], v[206:207]
	v_pk_mul_f32 v[208:209], v[68:69], v[106:107] op_sel_hi:[1,0]
	v_pk_mul_f32 v[210:211], v[70:71], v[106:107] op_sel_hi:[1,0]
	v_pk_mul_f32 v[208:209], v[184:185], v[208:209]
	v_pk_mul_f32 v[210:211], v[186:187], v[210:211]
	v_pk_mul_f32 v[212:213], v[72:73], v[106:107] op_sel_hi:[1,0]
	v_pk_mul_f32 v[214:215], v[74:75], v[106:107] op_sel_hi:[1,0]
	v_pk_mul_f32 v[212:213], v[188:189], v[212:213]
	v_pk_mul_f32 v[214:215], v[190:191], v[214:215]
	v_pk_mul_f32 v[216:217], v[76:77], v[106:107] op_sel_hi:[1,0]
	v_pk_mul_f32 v[218:219], v[78:79], v[106:107] op_sel_hi:[1,0]
	v_pk_mul_f32 v[216:217], v[192:193], v[216:217]
	v_pk_mul_f32 v[218:219], v[194:195], v[218:219]
	v_cvt_pk_bf16_f32 v220, v204, v205
	v_cvt_pk_bf16_f32 v221, v206, v207
	v_cvt_pk_bf16_f32 v222, v208, v209
	v_cvt_pk_bf16_f32 v223, v210, v211
	v_cvt_pk_bf16_f32 v224, v212, v213
	v_cvt_pk_bf16_f32 v225, v214, v215
	v_cvt_pk_bf16_f32 v226, v216, v217
	v_cvt_pk_bf16_f32 v227, v218, v219
	global_store_dwordx4 v198, v[220:223], s[26:27] offset:2048
	global_store_dwordx4 v198, v[224:227], s[26:27] offset:3072
	s_add_u32 s26, s26, s99
	s_addc_u32 s27, s27, 0
	s_cmp_lg_u32 s11, 0
	s_cbranch_scc0 .Lx8_done
	s_branch .Lx8_half0
.Lx8_done:
.LBB0_1042:
	s_mov_b64 s[6:7], 0
